# in-proj tail split by row halves (second CU of a pair takes rows 128..255): ai=1 super-phase MFMAs and A reads removed, second epilogue half skipped
# speedup vs baseline: 1.0026x; 1.0026x over previous
; template <class Epi, class Sched, bool ALIGN_EPI = false, bool SP2 = false>
; __device__ __forceinline__ void gemm_phase(PG8_LAS unsigned char* lds, const Gemm g, const Sched& S, const Epi& E) {
;     ...
;     for (;;) {
;         const bool has_next = S.next(ui + 1, nxt);
;         const char* nA = has_next ? (const char*)g.A + (size_t)nxt.pm * tstep : cA; const char* nB = has_next ? (const char*)g.Bt + (size_t)nxt.pn * tstep : cB;
;         for (int t = 0; t < nt; t += 2) {
;             const bool last = (t == nt - 2);
;             const char* a1 = cA + (size_t)(t + 1) * kstep;
;             const char* a2 = last ? nA : cA + (size_t)(t + 2) * kstep; const char* b2 = last ? nB : cB + (size_t)(t + 2) * kstep;
;             const char* a3 = a2 + kstep; const char* b3 = b2 + kstep;
;             if (last && has_next) S.a_ready(nxt);
.LBB0_213:
	s_ashr_i32 s19, s18, 31
	s_lshl_b64 s[20:21], s[18:19], 20
	s_add_u32 s20, s30, s20
	s_addc_u32 s21, s31, s21
	s_cmp_lg_u32 s27, 6
	s_cbranch_scc1 .Ltail_b
	s_lshr_b32 s80, s49, 7
	s_lshl_b32 s80, s80, 19
	s_add_u32 s20, s20, s80
	s_addc_u32 s21, s21, 0
.Ltail_b:
	s_and_b64 s[22:23], s[38:39], exec
	s_cselect_b32 s15, s21, s43
	s_cselect_b32 s19, s20, s42
	s_ashr_i32 s17, s16, 31
	s_lshl_b64 s[22:23], s[16:17], 20
	s_add_u32 s22, s4, s22
	s_addc_u32 s23, s5, s23
	s_and_b64 s[34:35], s[38:39], exec
	s_cselect_b32 s17, s23, s41
	s_cselect_b32 s37, s22, s40
	s_add_u32 s34, s42, 0x80080
	s_addc_u32 s35, s43, 0
	s_add_u32 s44, s40, 0x100
	v_mov_b32_e32 v2, 0
	s_addc_u32 s45, s41, 0
	s_mov_b32 s46, -2
	v_mov_b32_e32 v3, v2
	v_mov_b32_e32 v4, v2
	v_mov_b32_e32 v5, v2
	v_mov_b32_e32 v6, v2
	v_mov_b32_e32 v7, v2
	v_mov_b32_e32 v8, v2
	v_mov_b32_e32 v9, v2
	v_mov_b32_e32 v18, v2
	v_mov_b32_e32 v19, v2
	v_mov_b32_e32 v20, v2
	v_mov_b32_e32 v21, v2
	v_mov_b32_e32 v22, v2
	v_mov_b32_e32 v23, v2
	v_mov_b32_e32 v24, v2
	v_mov_b32_e32 v25, v2
	v_mov_b32_e32 v34, v2
	v_mov_b32_e32 v35, v2
	v_mov_b32_e32 v36, v2
	v_mov_b32_e32 v37, v2
	v_mov_b32_e32 v38, v2
	v_mov_b32_e32 v39, v2
	v_mov_b32_e32 v40, v2
	v_mov_b32_e32 v41, v2
	v_mov_b32_e32 v50, v2
	v_mov_b32_e32 v51, v2
	v_mov_b32_e32 v52, v2
	v_mov_b32_e32 v53, v2
	v_mov_b32_e32 v54, v2
	v_mov_b32_e32 v55, v2
	v_mov_b32_e32 v56, v2
	v_mov_b32_e32 v57, v2
	v_mov_b32_e32 v10, v2
	v_mov_b32_e32 v11, v2
	v_mov_b32_e32 v12, v2
	v_mov_b32_e32 v13, v2
	v_mov_b32_e32 v14, v2
	v_mov_b32_e32 v15, v2
	v_mov_b32_e32 v16, v2
	v_mov_b32_e32 v17, v2
	v_mov_b32_e32 v26, v2
	v_mov_b32_e32 v27, v2
	v_mov_b32_e32 v28, v2
	v_mov_b32_e32 v29, v2
	v_mov_b32_e32 v30, v2
	v_mov_b32_e32 v31, v2
	v_mov_b32_e32 v32, v2
	v_mov_b32_e32 v33, v2
	v_mov_b32_e32 v42, v2
	v_mov_b32_e32 v43, v2
	v_mov_b32_e32 v44, v2
	v_mov_b32_e32 v45, v2
	v_mov_b32_e32 v46, v2
	v_mov_b32_e32 v47, v2
	v_mov_b32_e32 v48, v2
	v_mov_b32_e32 v49, v2
	v_mov_b32_e32 v58, v2
	v_mov_b32_e32 v59, v2
	v_mov_b32_e32 v60, v2
	v_mov_b32_e32 v61, v2
	v_mov_b32_e32 v62, v2
	v_mov_b32_e32 v63, v2
	v_mov_b32_e32 v64, v2
	v_mov_b32_e32 v65, v2
	v_mov_b32_e32 v66, v2
	v_mov_b32_e32 v67, v2
	v_mov_b32_e32 v68, v2
	v_mov_b32_e32 v69, v2
	v_mov_b32_e32 v70, v2
	v_mov_b32_e32 v71, v2
	v_mov_b32_e32 v72, v2
	v_mov_b32_e32 v73, v2
	v_mov_b32_e32 v82, v2
	v_mov_b32_e32 v83, v2
	v_mov_b32_e32 v84, v2
	v_mov_b32_e32 v85, v2
	v_mov_b32_e32 v86, v2
	v_mov_b32_e32 v87, v2
	v_mov_b32_e32 v88, v2
	v_mov_b32_e32 v89, v2
	v_mov_b32_e32 v98, v2
	v_mov_b32_e32 v99, v2
	v_mov_b32_e32 v100, v2
	v_mov_b32_e32 v101, v2
	v_mov_b32_e32 v102, v2
	v_mov_b32_e32 v103, v2
	v_mov_b32_e32 v104, v2
	v_mov_b32_e32 v105, v2
	v_mov_b32_e32 v122, v2
	v_mov_b32_e32 v123, v2
	v_mov_b32_e32 v124, v2
	v_mov_b32_e32 v125, v2
	v_mov_b32_e32 v126, v2
	v_mov_b32_e32 v127, v2
	v_mov_b32_e32 v128, v2
	v_mov_b32_e32 v129, v2
	v_mov_b32_e32 v74, v2
	v_mov_b32_e32 v75, v2
	v_mov_b32_e32 v76, v2
	v_mov_b32_e32 v77, v2
	v_mov_b32_e32 v78, v2
	v_mov_b32_e32 v79, v2
	v_mov_b32_e32 v80, v2
	v_mov_b32_e32 v81, v2
	v_mov_b32_e32 v90, v2
	v_mov_b32_e32 v91, v2
	v_mov_b32_e32 v92, v2
	v_mov_b32_e32 v93, v2
	v_mov_b32_e32 v94, v2
	v_mov_b32_e32 v95, v2
	v_mov_b32_e32 v96, v2
	v_mov_b32_e32 v97, v2
	v_mov_b32_e32 v106, v2
	v_mov_b32_e32 v107, v2
	v_mov_b32_e32 v108, v2
	v_mov_b32_e32 v109, v2
	v_mov_b32_e32 v110, v2
	v_mov_b32_e32 v111, v2
	v_mov_b32_e32 v112, v2
	v_mov_b32_e32 v113, v2
	v_mov_b32_e32 v138, v2
	v_mov_b32_e32 v139, v2
	v_mov_b32_e32 v140, v2
	v_mov_b32_e32 v141, v2
	v_mov_b32_e32 v142, v2
	v_mov_b32_e32 v143, v2
	v_mov_b32_e32 v144, v2
	v_mov_b32_e32 v145, v2
	s_cmp_eq_u32 s27, 7
	s_cbranch_scc1 .Ltail_loop

; __device__ __forceinline__ unsigned cvt_pk_bf16(float lo, float hi) { unsigned r; asm volatile("v_cvt_pk_bf16_f32 %0, %1, %2" : "=v"(r) : "v"(lo), "v"(hi)); return r; }
;     __device__ __forceinline__ void operator()(const f32x4 (&acc)[2][2][4][2], const Unit& u, int wr, int wc, int fr, int fq) const {
;         const int row0 = u.pm * BM + wr * 64 + fr, col0 = wc * 32 + 8 * fq;
; #pragma unroll
;         for (int ai = 0; ai < 2; ++ai) {
;             f32x4 pa[4], pb[4];
; #pragma unroll
;             for (int m = 0; m < 4; ++m) { const f32x4* pp = (const f32x4*)(rowsq + (size_t)(row0 + ai * HALF + m * 16) * 32 + 8 * fq); pa[m] = pp[0]; pb[m] = pp[1]; }
; #pragma unroll
;             for (int m = 0; m < 4; ++m) { const int row = row0 + ai * HALF + m * 16; const f32x4 a = pa[m], b = pb[m];
;                 float sq = ((a[0] + a[1]) + (a[2] + a[3])) + ((b[0] + b[1]) + (b[2] + b[3])); sq += __shfl_xor(sq, 16); sq += __shfl_xor(sq, 32);
;                 const float rs = __builtin_amdgcn_rsqf(sq * inv_k + eps);
; #pragma unroll
;                 for (int bj = 0; bj < 2; ++bj) { const f32x4 v0 = acc[ai][bj][m][0] * rs, v1 = acc[ai][bj][m][1] * rs;
;                     u32x4 w; w.x = cvt_pk_bf16(v0[0], v0[1]); w.y = cvt_pk_bf16(v0[2], v0[3]); w.z = cvt_pk_bf16(v1[0], v1[1]); w.w = cvt_pk_bf16(v1[2], v1[3]);
;                     *(u32x4*)(O + ((size_t)(u.pn * 2 + bj) * Mrows + row) * HALF + col0) = w; } }
.LBB0_217:
	v_cmp_lt_i32_e32 vcc, v224, v219
	v_lshl_add_u32 v168, s36, 8, v176
	s_cmp_eq_u32 s27, 7
	s_cselect_b32 s80, 0x80, 0
	s_lshr_b32 s81, s49, 7
	s_mul_i32 s80, s80, s81
	v_add_u32_e32 v168, s80, v168
	v_ashrrev_i32_e32 v169, 31, v168
	v_cndmask_b32_e32 v114, v218, v224, vcc
	v_cmp_lt_i32_e32 vcc, v225, v219
	v_lshlrev_b32_e32 v180, 2, v114
	v_or_b32_e32 v174, 16, v168
	v_cndmask_b32_e32 v114, v218, v225, vcc
	v_lshlrev_b32_e32 v179, 2, v114
	v_lshlrev_b64 v[114:115], 7, v[168:169]
	v_lshl_add_u64 v[114:115], v[162:163], 0, v[114:115]
	global_load_dwordx4 v[182:185], v[114:115], off
	global_load_dwordx4 v[186:189], v[114:115], off offset:16
	v_ashrrev_i32_e32 v175, 31, v174
	v_lshlrev_b64 v[114:115], 7, v[174:175]
	v_lshl_add_u64 v[114:115], v[162:163], 0, v[114:115]
	global_load_dwordx4 v[146:149], v[114:115], off
	global_load_dwordx4 v[150:153], v[114:115], off offset:16
	v_or_b32_e32 v172, 32, v168
	v_ashrrev_i32_e32 v173, 31, v172
	v_lshlrev_b64 v[114:115], 7, v[172:173]
	v_lshl_add_u64 v[114:115], v[162:163], 0, v[114:115]
	global_load_dwordx4 v[134:137], v[114:115], off
	global_load_dwordx4 v[130:133], v[114:115], off offset:16
	v_or_b32_e32 v170, 48, v168
	v_ashrrev_i32_e32 v171, 31, v170
	v_lshlrev_b64 v[114:115], 7, v[170:171]
	v_lshl_add_u64 v[114:115], v[162:163], 0, v[114:115]
	global_load_dwordx4 v[118:121], v[114:115], off
	s_nop 0
	global_load_dwordx4 v[114:117], v[114:115], off offset:16
	s_lshl_b32 s14, s14, 1
	s_ashr_i32 s15, s14, 31
	s_lshl_b64 s[34:35], s[14:15], 14
	s_or_b32 s14, s14, 1
	s_ashr_i32 s15, s14, 31
	s_lshl_b64 s[36:37], s[14:15], 14
	s_andn2_b64 vcc, exec, s[38:39]
	s_waitcnt vmcnt(0)
	v_mov_b32_e32 v190, v182
	v_mov_b32_e32 v191, v186
	v_mov_b32_e32 v186, v183
	v_pk_add_f32 v[182:183], v[190:191], v[186:187]
	v_mov_b32_e32 v186, v184
	v_mov_b32_e32 v187, v188
	v_mov_b32_e32 v188, v185
	v_pk_add_f32 v[184:185], v[186:187], v[188:189]
	s_nop 0
	v_pk_add_f32 v[182:183], v[182:183], v[184:185]
	s_nop 0
	v_add_f32_e32 v181, v182, v183
	ds_bpermute_b32 v182, v180, v181
	s_waitcnt lgkmcnt(0)
	v_add_f32_e32 v181, v181, v182
	ds_bpermute_b32 v182, v179, v181
	s_waitcnt lgkmcnt(0)
	v_add_f32_e32 v181, v181, v182
	v_fmamk_f32 v181, v181, 0x3a000000, v215
	v_rsq_f32_e32 v182, v181
	s_nop 0
	v_pk_mul_f32 v[142:143], v[142:143], v[182:183] op_sel_hi:[1,0]
	v_pk_mul_f32 v[184:185], v[140:141], v[182:183] op_sel_hi:[1,0]
	v_pk_mul_f32 v[140:141], v[138:139], v[182:183] op_sel_hi:[1,0]
	v_cvt_pk_bf16_f32 v138, v142, v143
	v_lshl_add_u64 v[142:143], s[34:35], 0, v[168:169]
	v_lshlrev_b64 v[142:143], 8, v[142:143]
	v_pk_mul_f32 v[144:145], v[144:145], v[182:183] op_sel_hi:[1,0]
	v_lshl_add_u64 v[142:143], v[160:161], 0, v[142:143]
	v_cvt_pk_bf16_f32 v139, v144, v145
	v_pk_mul_f32 v[126:127], v[126:127], v[182:183] op_sel_hi:[1,0]
	v_cvt_pk_bf16_f32 v140, v140, v141
	v_cvt_pk_bf16_f32 v141, v184, v185
	global_store_dwordx4 v[142:143], v[138:141], off
	v_pk_mul_f32 v[128:129], v[128:129], v[182:183] op_sel_hi:[1,0]
	s_nop 0
	v_pk_mul_f32 v[138:139], v[124:125], v[182:183] op_sel_hi:[1,0]
	v_pk_mul_f32 v[124:125], v[122:123], v[182:183] op_sel_hi:[1,0]
	v_cvt_pk_bf16_f32 v122, v126, v127
	v_lshl_add_u64 v[126:127], s[36:37], 0, v[168:169]
	v_lshlrev_b64 v[126:127], 8, v[126:127]
	v_cvt_pk_bf16_f32 v123, v128, v129
	v_cvt_pk_bf16_f32 v124, v124, v125
	v_cvt_pk_bf16_f32 v125, v138, v139
	v_lshl_add_u64 v[126:127], v[160:161], 0, v[126:127]
	global_store_dwordx4 v[126:127], v[122:125], off
	s_nop 1
	v_mov_b32_e32 v122, v146
	v_mov_b32_e32 v123, v150
	v_mov_b32_e32 v150, v147
	v_mov_b32_e32 v124, v148
	v_mov_b32_e32 v125, v152
	v_mov_b32_e32 v152, v149
	v_pk_add_f32 v[122:123], v[122:123], v[150:151]
	v_pk_add_f32 v[124:125], v[124:125], v[152:153]
	s_nop 0
	v_pk_add_f32 v[122:123], v[122:123], v[124:125]
	s_nop 0
	v_add_f32_e32 v122, v122, v123
	ds_bpermute_b32 v123, v180, v122
	s_waitcnt lgkmcnt(0)
	v_add_f32_e32 v122, v122, v123
	ds_bpermute_b32 v123, v179, v122
	s_waitcnt lgkmcnt(0)
	v_add_f32_e32 v122, v122, v123
	v_fmamk_f32 v122, v122, 0x3a000000, v215
	v_rsq_f32_e32 v122, v122
	s_nop 0
	v_pk_mul_f32 v[110:111], v[110:111], v[122:123] op_sel_hi:[1,0]
	v_pk_mul_f32 v[124:125], v[108:109], v[122:123] op_sel_hi:[1,0]
	v_pk_mul_f32 v[108:109], v[106:107], v[122:123] op_sel_hi:[1,0]
	v_cvt_pk_bf16_f32 v106, v110, v111
	v_lshl_add_u64 v[110:111], s[34:35], 0, v[174:175]
	v_lshlrev_b64 v[110:111], 8, v[110:111]
	v_pk_mul_f32 v[112:113], v[112:113], v[122:123] op_sel_hi:[1,0]
	v_lshl_add_u64 v[110:111], v[160:161], 0, v[110:111]
	v_cvt_pk_bf16_f32 v107, v112, v113
	v_pk_mul_f32 v[102:103], v[102:103], v[122:123] op_sel_hi:[1,0]
	v_cvt_pk_bf16_f32 v108, v108, v109
	v_cvt_pk_bf16_f32 v109, v124, v125
	global_store_dwordx4 v[110:111], v[106:109], off
	v_pk_mul_f32 v[104:105], v[104:105], v[122:123] op_sel_hi:[1,0]
	s_nop 0
	v_pk_mul_f32 v[106:107], v[100:101], v[122:123] op_sel_hi:[1,0]
	v_pk_mul_f32 v[100:101], v[98:99], v[122:123] op_sel_hi:[1,0]
	v_cvt_pk_bf16_f32 v98, v102, v103
	v_lshl_add_u64 v[102:103], s[36:37], 0, v[174:175]
	v_lshlrev_b64 v[102:103], 8, v[102:103]
	v_cvt_pk_bf16_f32 v99, v104, v105
	v_cvt_pk_bf16_f32 v100, v100, v101
	v_cvt_pk_bf16_f32 v101, v106, v107
	v_lshl_add_u64 v[102:103], v[160:161], 0, v[102:103]
	global_store_dwordx4 v[102:103], v[98:101], off
	v_add_u32_e32 v104, 0x80, v168
	v_ashrrev_i32_e32 v105, 31, v104
	v_mov_b32_e32 v98, v134
	v_mov_b32_e32 v99, v130
	v_mov_b32_e32 v130, v135
	v_mov_b32_e32 v100, v136
	v_mov_b32_e32 v101, v132
	v_mov_b32_e32 v132, v137
	v_pk_add_f32 v[98:99], v[98:99], v[130:131]
	v_pk_add_f32 v[100:101], v[100:101], v[132:133]
	s_nop 0
	v_pk_add_f32 v[98:99], v[98:99], v[100:101]
	s_nop 0
	v_add_f32_e32 v98, v98, v99
	ds_bpermute_b32 v99, v180, v98
	s_waitcnt lgkmcnt(0)
; __device__ __forceinline__ unsigned cvt_pk_bf16(float lo, float hi) { unsigned r; asm volatile("v_cvt_pk_bf16_f32 %0, %1, %2" : "=v"(r) : "v"(lo), "v"(hi)); return r; }
;     __device__ __forceinline__ void operator()(const f32x4 (&acc)[2][2][4][2], const Unit& u, int wr, int wc, int fr, int fq) const {
;     ...
;             for (int m = 0; m < 4; ++m) { const int row = row0 + ai * HALF + m * 16; const f32x4 a = pa[m], b = pb[m];
;                 float sq = ((a[0] + a[1]) + (a[2] + a[3])) + ((b[0] + b[1]) + (b[2] + b[3])); sq += __shfl_xor(sq, 16); sq += __shfl_xor(sq, 32);
;                 const float rs = __builtin_amdgcn_rsqf(sq * inv_k + eps);
; #pragma unroll
;                 for (int bj = 0; bj < 2; ++bj) { const f32x4 v0 = acc[ai][bj][m][0] * rs, v1 = acc[ai][bj][m][1] * rs;
;                     u32x4 w; w.x = cvt_pk_bf16(v0[0], v0[1]); w.y = cvt_pk_bf16(v0[2], v0[3]); w.z = cvt_pk_bf16(v1[0], v1[1]); w.w = cvt_pk_bf16(v1[2], v1[3]);
;                     *(u32x4*)(O + ((size_t)(u.pn * 2 + bj) * Mrows + row) * HALF + col0) = w; } }
	v_add_f32_e32 v98, v98, v99
	ds_bpermute_b32 v99, v179, v98
	s_waitcnt lgkmcnt(0)
	v_add_f32_e32 v98, v98, v99
	v_fmamk_f32 v98, v98, 0x3a000000, v215
	v_rsq_f32_e32 v98, v98
	s_nop 0
	v_pk_mul_f32 v[94:95], v[94:95], v[98:99] op_sel_hi:[1,0]
	v_pk_mul_f32 v[100:101], v[92:93], v[98:99] op_sel_hi:[1,0]
	v_pk_mul_f32 v[92:93], v[90:91], v[98:99] op_sel_hi:[1,0]
	v_cvt_pk_bf16_f32 v90, v94, v95
	v_lshl_add_u64 v[94:95], s[34:35], 0, v[172:173]
	v_lshlrev_b64 v[94:95], 8, v[94:95]
	v_pk_mul_f32 v[96:97], v[96:97], v[98:99] op_sel_hi:[1,0]
	v_lshl_add_u64 v[94:95], v[160:161], 0, v[94:95]
	v_cvt_pk_bf16_f32 v91, v96, v97
	v_pk_mul_f32 v[86:87], v[86:87], v[98:99] op_sel_hi:[1,0]
	v_cvt_pk_bf16_f32 v92, v92, v93
	v_cvt_pk_bf16_f32 v93, v100, v101
	global_store_dwordx4 v[94:95], v[90:93], off
	v_pk_mul_f32 v[88:89], v[88:89], v[98:99] op_sel_hi:[1,0]
	s_nop 0
	v_pk_mul_f32 v[90:91], v[84:85], v[98:99] op_sel_hi:[1,0]
	v_pk_mul_f32 v[84:85], v[82:83], v[98:99] op_sel_hi:[1,0]
	v_cvt_pk_bf16_f32 v82, v86, v87
	v_lshl_add_u64 v[86:87], s[36:37], 0, v[172:173]
	v_lshlrev_b64 v[86:87], 8, v[86:87]
	v_cvt_pk_bf16_f32 v83, v88, v89
	v_cvt_pk_bf16_f32 v84, v84, v85
	v_cvt_pk_bf16_f32 v85, v90, v91
	v_lshl_add_u64 v[86:87], v[160:161], 0, v[86:87]
	global_store_dwordx4 v[86:87], v[82:85], off
	v_add_u32_e32 v86, 0x90, v168
	v_ashrrev_i32_e32 v87, 31, v86
	v_mov_b32_e32 v82, v118
	v_mov_b32_e32 v83, v114
	v_mov_b32_e32 v114, v119
	v_mov_b32_e32 v84, v120
	v_mov_b32_e32 v85, v116
	v_mov_b32_e32 v116, v121
	v_pk_add_f32 v[82:83], v[82:83], v[114:115]
	v_pk_add_f32 v[84:85], v[84:85], v[116:117]
	s_nop 0
	v_pk_add_f32 v[82:83], v[82:83], v[84:85]
	s_nop 0
	v_add_f32_e32 v82, v82, v83
	ds_bpermute_b32 v83, v180, v82
	s_waitcnt lgkmcnt(0)
	v_add_f32_e32 v82, v82, v83
	ds_bpermute_b32 v83, v179, v82
	s_waitcnt lgkmcnt(0)
	v_add_f32_e32 v82, v82, v83
	v_fmamk_f32 v82, v82, 0x3a000000, v215
	v_rsq_f32_e32 v82, v82
	s_nop 0
	v_pk_mul_f32 v[78:79], v[78:79], v[82:83] op_sel_hi:[1,0]
	v_pk_mul_f32 v[84:85], v[76:77], v[82:83] op_sel_hi:[1,0]
	v_pk_mul_f32 v[76:77], v[74:75], v[82:83] op_sel_hi:[1,0]
	v_cvt_pk_bf16_f32 v74, v78, v79
	v_lshl_add_u64 v[78:79], s[34:35], 0, v[170:171]
	v_lshlrev_b64 v[78:79], 8, v[78:79]
	v_pk_mul_f32 v[80:81], v[80:81], v[82:83] op_sel_hi:[1,0]
	v_lshl_add_u64 v[78:79], v[160:161], 0, v[78:79]
	v_cvt_pk_bf16_f32 v75, v80, v81
	v_pk_mul_f32 v[70:71], v[70:71], v[82:83] op_sel_hi:[1,0]
	v_cvt_pk_bf16_f32 v76, v76, v77
	v_cvt_pk_bf16_f32 v77, v84, v85
	global_store_dwordx4 v[78:79], v[74:77], off
	v_pk_mul_f32 v[72:73], v[72:73], v[82:83] op_sel_hi:[1,0]
	v_add_u32_e32 v84, 0xa0, v168
	v_pk_mul_f32 v[74:75], v[68:69], v[82:83] op_sel_hi:[1,0]
	v_pk_mul_f32 v[68:69], v[66:67], v[82:83] op_sel_hi:[1,0]
	v_cvt_pk_bf16_f32 v66, v70, v71
	v_lshl_add_u64 v[70:71], s[36:37], 0, v[170:171]
	v_lshlrev_b64 v[70:71], 8, v[70:71]
	v_cvt_pk_bf16_f32 v67, v72, v73
	v_lshl_add_u64 v[70:71], v[160:161], 0, v[70:71]
	v_cvt_pk_bf16_f32 v68, v68, v69
	v_cvt_pk_bf16_f32 v69, v74, v75
	global_store_dwordx4 v[70:71], v[66:69], off
	s_cmp_lg_u32 s27, 7
	s_cbranch_scc1 .Ltail_c
	s_mov_b64 s[34:35], -1
	s_branch .LBB0_210
.Ltail_c:
	v_ashrrev_i32_e32 v85, 31, v84
	v_add_u32_e32 v82, 0xb0, v168
	v_lshlrev_b64 v[66:67], 7, v[104:105]
	v_lshl_add_u64 v[66:67], v[162:163], 0, v[66:67]
	global_load_dwordx4 v[88:91], v[66:67], off
	global_load_dwordx4 v[92:95], v[66:67], off offset:16
	v_lshlrev_b64 v[66:67], 7, v[86:87]
	v_lshl_add_u64 v[66:67], v[162:163], 0, v[66:67]
	global_load_dwordx4 v[96:99], v[66:67], off
	global_load_dwordx4 v[100:103], v[66:67], off offset:16
	v_lshlrev_b64 v[66:67], 7, v[84:85]
	v_lshl_add_u64 v[66:67], v[162:163], 0, v[66:67]
	global_load_dwordx4 v[78:81], v[66:67], off
	global_load_dwordx4 v[74:77], v[66:67], off offset:16
	v_ashrrev_i32_e32 v83, 31, v82
	v_lshlrev_b64 v[66:67], 7, v[82:83]
	v_lshl_add_u64 v[66:67], v[162:163], 0, v[66:67]
	global_load_dwordx4 v[70:73], v[66:67], off
	s_nop 0
	global_load_dwordx4 v[66:69], v[66:67], off offset:16
	s_waitcnt vmcnt(7)
	v_mov_b32_e32 v106, v88
	s_waitcnt vmcnt(6)
	v_mov_b32_e32 v107, v92
	v_mov_b32_e32 v92, v89
	v_pk_add_f32 v[88:89], v[106:107], v[92:93]
	v_mov_b32_e32 v92, v90
	v_mov_b32_e32 v93, v94
	v_mov_b32_e32 v94, v91
	v_pk_add_f32 v[90:91], v[92:93], v[94:95]
	s_nop 0
	v_pk_add_f32 v[88:89], v[88:89], v[90:91]
	s_nop 0
	v_add_f32_e32 v88, v88, v89
	ds_bpermute_b32 v89, v180, v88
	s_waitcnt lgkmcnt(0)
	v_add_f32_e32 v88, v88, v89
	ds_bpermute_b32 v89, v179, v88
	s_waitcnt lgkmcnt(0)
	v_add_f32_e32 v88, v88, v89
	v_fmamk_f32 v88, v88, 0x3a000000, v215
	v_rsq_f32_e32 v88, v88
	s_nop 0
	v_pk_mul_f32 v[62:63], v[62:63], v[88:89] op_sel_hi:[1,0]
	v_pk_mul_f32 v[90:91], v[60:61], v[88:89] op_sel_hi:[1,0]
	v_pk_mul_f32 v[60:61], v[58:59], v[88:89] op_sel_hi:[1,0]
	v_cvt_pk_bf16_f32 v58, v62, v63
	v_lshl_add_u64 v[62:63], s[34:35], 0, v[104:105]
	v_lshlrev_b64 v[62:63], 8, v[62:63]
	v_pk_mul_f32 v[64:65], v[64:65], v[88:89] op_sel_hi:[1,0]
	v_lshl_add_u64 v[62:63], v[160:161], 0, v[62:63]
	v_cvt_pk_bf16_f32 v59, v64, v65
	v_pk_mul_f32 v[54:55], v[54:55], v[88:89] op_sel_hi:[1,0]
	v_cvt_pk_bf16_f32 v60, v60, v61
	v_cvt_pk_bf16_f32 v61, v90, v91
	global_store_dwordx4 v[62:63], v[58:61], off
	v_pk_mul_f32 v[56:57], v[56:57], v[88:89] op_sel_hi:[1,0]
	s_nop 0
	v_pk_mul_f32 v[58:59], v[52:53], v[88:89] op_sel_hi:[1,0]
	v_pk_mul_f32 v[52:53], v[50:51], v[88:89] op_sel_hi:[1,0]
	v_cvt_pk_bf16_f32 v50, v54, v55
	v_lshl_add_u64 v[54:55], s[36:37], 0, v[104:105]
	v_lshlrev_b64 v[54:55], 8, v[54:55]
	v_cvt_pk_bf16_f32 v51, v56, v57
	v_cvt_pk_bf16_f32 v52, v52, v53
	v_cvt_pk_bf16_f32 v53, v58, v59
	v_lshl_add_u64 v[54:55], v[160:161], 0, v[54:55]
	global_store_dwordx4 v[54:55], v[50:53], off
	s_waitcnt vmcnt(7)
; __device__ __forceinline__ unsigned cvt_pk_bf16(float lo, float hi) { unsigned r; asm volatile("v_cvt_pk_bf16_f32 %0, %1, %2" : "=v"(r) : "v"(lo), "v"(hi)); return r; }
;     __device__ __forceinline__ void operator()(const f32x4 (&acc)[2][2][4][2], const Unit& u, int wr, int wc, int fr, int fq) const {
;     ...
;             for (int m = 0; m < 4; ++m) { const int row = row0 + ai * HALF + m * 16; const f32x4 a = pa[m], b = pb[m];
;                 float sq = ((a[0] + a[1]) + (a[2] + a[3])) + ((b[0] + b[1]) + (b[2] + b[3])); sq += __shfl_xor(sq, 16); sq += __shfl_xor(sq, 32);
;                 const float rs = __builtin_amdgcn_rsqf(sq * inv_k + eps);
; #pragma unroll
;                 for (int bj = 0; bj < 2; ++bj) { const f32x4 v0 = acc[ai][bj][m][0] * rs, v1 = acc[ai][bj][m][1] * rs;
;                     u32x4 w; w.x = cvt_pk_bf16(v0[0], v0[1]); w.y = cvt_pk_bf16(v0[2], v0[3]); w.z = cvt_pk_bf16(v1[0], v1[1]); w.w = cvt_pk_bf16(v1[2], v1[3]);
;                     *(u32x4*)(O + ((size_t)(u.pn * 2 + bj) * Mrows + row) * HALF + col0) = w; } }
	s_nop 0
	v_mov_b32_e32 v50, v96
	s_waitcnt vmcnt(6)
	v_mov_b32_e32 v51, v100
	v_mov_b32_e32 v100, v97
	v_mov_b32_e32 v52, v98
	v_mov_b32_e32 v53, v102
	v_mov_b32_e32 v102, v99
	v_pk_add_f32 v[50:51], v[50:51], v[100:101]
	v_pk_add_f32 v[52:53], v[52:53], v[102:103]
	s_nop 0
	v_pk_add_f32 v[50:51], v[50:51], v[52:53]
	s_nop 0
	v_add_f32_e32 v50, v50, v51
	ds_bpermute_b32 v51, v180, v50
	s_waitcnt lgkmcnt(0)
	v_add_f32_e32 v50, v50, v51
	ds_bpermute_b32 v51, v179, v50
	s_waitcnt lgkmcnt(0)
	v_add_f32_e32 v50, v50, v51
	v_fmamk_f32 v50, v50, 0x3a000000, v215
	v_rsq_f32_e32 v50, v50
	s_nop 0
	v_pk_mul_f32 v[46:47], v[46:47], v[50:51] op_sel_hi:[1,0]
	v_pk_mul_f32 v[52:53], v[44:45], v[50:51] op_sel_hi:[1,0]
	v_pk_mul_f32 v[44:45], v[42:43], v[50:51] op_sel_hi:[1,0]
	v_cvt_pk_bf16_f32 v42, v46, v47
	v_lshl_add_u64 v[46:47], s[34:35], 0, v[86:87]
	v_lshlrev_b64 v[46:47], 8, v[46:47]
	v_pk_mul_f32 v[48:49], v[48:49], v[50:51] op_sel_hi:[1,0]
	v_lshl_add_u64 v[46:47], v[160:161], 0, v[46:47]
	v_cvt_pk_bf16_f32 v43, v48, v49
	v_pk_mul_f32 v[38:39], v[38:39], v[50:51] op_sel_hi:[1,0]
	v_cvt_pk_bf16_f32 v44, v44, v45
	v_cvt_pk_bf16_f32 v45, v52, v53
	global_store_dwordx4 v[46:47], v[42:45], off
	v_pk_mul_f32 v[40:41], v[40:41], v[50:51] op_sel_hi:[1,0]
	s_nop 0
	v_pk_mul_f32 v[42:43], v[36:37], v[50:51] op_sel_hi:[1,0]
	v_pk_mul_f32 v[36:37], v[34:35], v[50:51] op_sel_hi:[1,0]
	v_cvt_pk_bf16_f32 v34, v38, v39
	v_lshl_add_u64 v[38:39], s[36:37], 0, v[86:87]
	v_lshlrev_b64 v[38:39], 8, v[38:39]
	v_cvt_pk_bf16_f32 v35, v40, v41
	v_cvt_pk_bf16_f32 v36, v36, v37
	v_cvt_pk_bf16_f32 v37, v42, v43
	v_lshl_add_u64 v[38:39], v[160:161], 0, v[38:39]
	global_store_dwordx4 v[38:39], v[34:37], off
	s_waitcnt vmcnt(7)
	s_nop 0
	v_mov_b32_e32 v34, v78
	s_waitcnt vmcnt(6)
	v_mov_b32_e32 v35, v74
	v_mov_b32_e32 v74, v79
	v_mov_b32_e32 v36, v80
	v_mov_b32_e32 v37, v76
	v_mov_b32_e32 v76, v81
	v_pk_add_f32 v[34:35], v[34:35], v[74:75]
	v_pk_add_f32 v[36:37], v[36:37], v[76:77]
	s_nop 0
	v_pk_add_f32 v[34:35], v[34:35], v[36:37]
	s_nop 0
	v_add_f32_e32 v34, v34, v35
	ds_bpermute_b32 v35, v180, v34
	s_waitcnt lgkmcnt(0)
	v_add_f32_e32 v34, v34, v35
	ds_bpermute_b32 v35, v179, v34
	s_waitcnt lgkmcnt(0)
	v_add_f32_e32 v34, v34, v35
	v_fmamk_f32 v34, v34, 0x3a000000, v215
	v_rsq_f32_e32 v34, v34
	s_nop 0
	v_pk_mul_f32 v[30:31], v[30:31], v[34:35] op_sel_hi:[1,0]
	v_pk_mul_f32 v[36:37], v[28:29], v[34:35] op_sel_hi:[1,0]
	v_pk_mul_f32 v[28:29], v[26:27], v[34:35] op_sel_hi:[1,0]
	v_cvt_pk_bf16_f32 v26, v30, v31
	v_lshl_add_u64 v[30:31], s[34:35], 0, v[84:85]
	v_lshlrev_b64 v[30:31], 8, v[30:31]
	v_pk_mul_f32 v[32:33], v[32:33], v[34:35] op_sel_hi:[1,0]
	v_lshl_add_u64 v[30:31], v[160:161], 0, v[30:31]
	v_cvt_pk_bf16_f32 v27, v32, v33
	v_pk_mul_f32 v[22:23], v[22:23], v[34:35] op_sel_hi:[1,0]
	v_cvt_pk_bf16_f32 v28, v28, v29
	v_cvt_pk_bf16_f32 v29, v36, v37
	global_store_dwordx4 v[30:31], v[26:29], off
	v_pk_mul_f32 v[24:25], v[24:25], v[34:35] op_sel_hi:[1,0]
	s_nop 0
	v_pk_mul_f32 v[26:27], v[20:21], v[34:35] op_sel_hi:[1,0]
	v_pk_mul_f32 v[20:21], v[18:19], v[34:35] op_sel_hi:[1,0]
	v_cvt_pk_bf16_f32 v18, v22, v23
	v_lshl_add_u64 v[22:23], s[36:37], 0, v[84:85]
	v_lshlrev_b64 v[22:23], 8, v[22:23]
	v_cvt_pk_bf16_f32 v19, v24, v25
	v_cvt_pk_bf16_f32 v20, v20, v21
	v_cvt_pk_bf16_f32 v21, v26, v27
	v_lshl_add_u64 v[22:23], v[160:161], 0, v[22:23]
	global_store_dwordx4 v[22:23], v[18:21], off
	s_waitcnt vmcnt(7)
	s_nop 0
	v_mov_b32_e32 v18, v70
	s_waitcnt vmcnt(6)
	v_mov_b32_e32 v19, v66
	v_mov_b32_e32 v66, v71
	v_mov_b32_e32 v20, v72
	v_mov_b32_e32 v21, v68
	v_mov_b32_e32 v68, v73
	v_pk_add_f32 v[18:19], v[18:19], v[66:67]
	v_pk_add_f32 v[20:21], v[20:21], v[68:69]
	s_nop 0
	v_pk_add_f32 v[18:19], v[18:19], v[20:21]
	s_nop 0
	v_add_f32_e32 v18, v18, v19
	ds_bpermute_b32 v19, v180, v18
	s_waitcnt lgkmcnt(0)
	v_add_f32_e32 v18, v18, v19
	ds_bpermute_b32 v19, v179, v18
	s_waitcnt lgkmcnt(0)
	v_add_f32_e32 v18, v18, v19
	v_fmamk_f32 v18, v18, 0x3a000000, v215
	v_rsq_f32_e32 v18, v18
	s_nop 0
	v_pk_mul_f32 v[14:15], v[14:15], v[18:19] op_sel_hi:[1,0]
	v_pk_mul_f32 v[20:21], v[12:13], v[18:19] op_sel_hi:[1,0]
	v_pk_mul_f32 v[12:13], v[10:11], v[18:19] op_sel_hi:[1,0]
	v_cvt_pk_bf16_f32 v10, v14, v15
	v_lshl_add_u64 v[14:15], s[34:35], 0, v[82:83]
	v_lshlrev_b64 v[14:15], 8, v[14:15]
	v_pk_mul_f32 v[16:17], v[16:17], v[18:19] op_sel_hi:[1,0]
	v_lshl_add_u64 v[14:15], v[160:161], 0, v[14:15]
	v_cvt_pk_bf16_f32 v11, v16, v17
	v_pk_mul_f32 v[6:7], v[6:7], v[18:19] op_sel_hi:[1,0]
	v_cvt_pk_bf16_f32 v12, v12, v13
	v_cvt_pk_bf16_f32 v13, v20, v21
	global_store_dwordx4 v[14:15], v[10:13], off
	v_pk_mul_f32 v[8:9], v[8:9], v[18:19] op_sel_hi:[1,0]
	s_mov_b64 s[34:35], -1
	v_pk_mul_f32 v[10:11], v[4:5], v[18:19] op_sel_hi:[1,0]
	v_pk_mul_f32 v[4:5], v[2:3], v[18:19] op_sel_hi:[1,0]
	v_cvt_pk_bf16_f32 v2, v6, v7
	v_lshl_add_u64 v[6:7], s[36:37], 0, v[82:83]
	v_lshlrev_b64 v[6:7], 8, v[6:7]
	v_lshl_add_u64 v[6:7], v[160:161], 0, v[6:7]
	v_cvt_pk_bf16_f32 v3, v8, v9
	v_cvt_pk_bf16_f32 v4, v4, v5
	v_cvt_pk_bf16_f32 v5, v10, v11
	global_store_dwordx4 v[6:7], v[2:5], off
	s_cbranch_vccnz .LBB0_210
	s_andn2_b64 vcc, exec, s[0:1]
	s_cbranch_vccnz .LBB0_209
	s_barrier
	s_branch .LBB0_209
; #define PG8_STAGE(bufoff, gbase, voff) do { _Pragma("unroll") for (int _i = 0; _i < 2; ++_i) \
;         __builtin_amdgcn_global_load_lds((const unsigned*)((const char*)(gbase) + (voff)[_i]), (PG8_LAS unsigned*)(lds + (bufoff) + ldsw + _i * 8192), 16, 0, 0); } while (0)
; #define PG8_LDA(dst, b, h) do { _Pragma("unroll") for (int m = 0; m < 4; ++m) _Pragma("unroll") for (int k = 0; k < 2; ++k) dst[m][k] = *(const PG8_LAS bf16x8*)(lds + PG8_SA(b, h) + aoff + m * 2048 + k * 1024); } while (0)
; #define PG8_LDB(dst, b, h) do { _Pragma("unroll") for (int n = 0; n < 2; ++n) _Pragma("unroll") for (int k = 0; k < 2; ++k) dst[n][k] = *(const PG8_LAS bf16x8*)(lds + PG8_SB(b, h) + boff + n * 2048 + k * 1024); } while (0)
; #define PG8_MMA(ai, bj, At, Bt) do { __builtin_amdgcn_s_setprio(1); _Pragma("unroll") for (int m = 0; m < 4; ++m) _Pragma("unroll") for (int n = 0; n < 2; ++n) _Pragma("unroll") for (int k = 0; k < 2; ++k) \
;         acc[ai][bj][m][n] = __builtin_amdgcn_mfma_f32_16x16x32_bf16(Bt[n][k], At[m][k], acc[ai][bj][m][n], 0, 0, 0); __builtin_amdgcn_s_setprio(0); } while (0)
; #define PG8_WAIT_V(n) asm volatile("s_waitcnt vmcnt(" #n ")" ::: "memory")
; #define PG8_WAIT_L(n) asm volatile("s_waitcnt lgkmcnt(" #n ")" ::: "memory")
; #define PG8_BAR __builtin_amdgcn_s_barrier()
; #define PG8_SCHED __builtin_amdgcn_sched_barrier(0)
; template <class Epi, class Sched, bool ALIGN_EPI = false, bool SP2 = false>
; __device__ __forceinline__ void gemm_phase(PG8_LAS unsigned char* lds, const Gemm g, const Sched& S, const Epi& E) {
;     ...
;             if constexpr (SP2) {
;             PG8_LDB(B0, 0, 0); PG8_LDB(B1, 0, 1); PG8_SCHED; PG8_LDA(At, 0, 0); PG8_STAGE(PG8_SA(1, 1), a1 + hstep, voffA);
;             PG8_WAIT_V(8); PG8_WAIT_L(0); PG8_BAR; PG8_MMA(0, 0, At, B0); PG8_MMA(0, 1, At, B1); PG8_BAR; PG8_SCHED;
;             PG8_LDA(At, 0, 1); PG8_STAGE(PG8_SB(0, 0), b2, voffB); PG8_STAGE(PG8_SB(0, 1), b2 + hstep, voffB); PG8_STAGE(PG8_SA(0, 0), a2, voffA);
;             PG8_WAIT_V(8); PG8_WAIT_L(0); PG8_BAR; PG8_MMA(1, 0, At, B0); PG8_MMA(1, 1, At, B1); PG8_BAR; PG8_SCHED;
.Ltail_loop:
	v_add_u32_e32 v134, s88, v177
	v_add_u32_e32 v172, s89, v177
	ds_read_b128 v[114:117], v134
	ds_read_b128 v[118:121], v134 offset:1024
	ds_read_b128 v[130:133], v134 offset:2048
	ds_read_b128 v[134:137], v134 offset:3072
	ds_read_b128 v[146:149], v172
	ds_read_b128 v[150:153], v172 offset:1024
	ds_read_b128 v[168:171], v172 offset:2048
	ds_read_b128 v[172:175], v172 offset:3072
	s_add_u32 s40, s34, 0xfff80080
	s_addc_u32 s41, s35, -1
	s_cmp_eq_u32 s46, 28
	s_cselect_b32 s43, s15, s41
	s_cselect_b32 s42, s19, s40
	s_cselect_b32 s41, s17, s45
	s_cselect_b32 s40, s37, s44
	v_lshl_add_u64 v[204:205], s[34:35], 0, v[164:165]
	s_add_i32 m0, s8, 0xc000
	ds_read_b128 v[180:183], v178
	ds_read_b128 v[184:187], v178 offset:1024
	ds_read_b128 v[188:191], v178 offset:2048
	ds_read_b128 v[192:195], v178 offset:3072
	ds_read_b128 v[196:199], v178 offset:4096
	ds_read_b128 v[200:203], v178 offset:5120
	ds_read_b128 v[208:211], v178 offset:6144
	ds_read_b128 v[230:233], v178 offset:7168
	global_load_lds_dwordx4 v[204:205], off
	v_lshl_add_u64 v[204:205], s[34:35], 0, v[166:167]
	s_add_i32 m0, s8, 0xe000
	s_nop 0
	global_load_lds_dwordx4 v[204:205], off
	s_waitcnt vmcnt(8)
	s_waitcnt lgkmcnt(0)
	s_barrier
	s_setprio 1
	s_waitcnt lgkmcnt(0)
	v_mfma_f32_16x16x32_bf16 v[142:145], v[114:117], v[180:183], v[142:145]
	v_mfma_f32_16x16x32_bf16 v[138:141], v[130:133], v[180:183], v[138:141]
	v_mfma_f32_16x16x32_bf16 v[110:113], v[114:117], v[188:191], v[110:113]
	v_mfma_f32_16x16x32_bf16 v[106:109], v[130:133], v[188:191], v[106:109]
	v_mfma_f32_16x16x32_bf16 v[94:97], v[114:117], v[196:199], v[94:97]
	v_mfma_f32_16x16x32_bf16 v[90:93], v[130:133], v[196:199], v[90:93]
	v_mfma_f32_16x16x32_bf16 v[78:81], v[114:117], v[208:211], v[78:81]
	v_mfma_f32_16x16x32_bf16 v[74:77], v[130:133], v[208:211], v[74:77]
	v_mfma_f32_16x16x32_bf16 v[142:145], v[118:121], v[184:187], v[142:145]
	v_mfma_f32_16x16x32_bf16 v[138:141], v[134:137], v[184:187], v[138:141]
	v_mfma_f32_16x16x32_bf16 v[110:113], v[118:121], v[192:195], v[110:113]
	v_mfma_f32_16x16x32_bf16 v[106:109], v[134:137], v[192:195], v[106:109]
	v_mfma_f32_16x16x32_bf16 v[94:97], v[118:121], v[200:203], v[94:97]
	v_mfma_f32_16x16x32_bf16 v[90:93], v[134:137], v[200:203], v[90:93]
	v_mfma_f32_16x16x32_bf16 v[78:81], v[118:121], v[230:233], v[78:81]
	v_mfma_f32_16x16x32_bf16 v[74:77], v[134:137], v[230:233], v[74:77]
	s_setprio 0
	s_setprio 1
	v_mfma_f32_16x16x32_bf16 v[126:129], v[146:149], v[180:183], v[126:129]
	v_mfma_f32_16x16x32_bf16 v[122:125], v[168:171], v[180:183], v[122:125]
	v_mfma_f32_16x16x32_bf16 v[102:105], v[146:149], v[188:191], v[102:105]
	v_mfma_f32_16x16x32_bf16 v[98:101], v[168:171], v[188:191], v[98:101]
	v_mfma_f32_16x16x32_bf16 v[86:89], v[146:149], v[196:199], v[86:89]
	v_mfma_f32_16x16x32_bf16 v[82:85], v[168:171], v[196:199], v[82:85]
	v_mfma_f32_16x16x32_bf16 v[70:73], v[146:149], v[208:211], v[70:73]
	v_mfma_f32_16x16x32_bf16 v[66:69], v[168:171], v[208:211], v[66:69]
	v_mfma_f32_16x16x32_bf16 v[126:129], v[150:153], v[184:187], v[126:129]
	v_mfma_f32_16x16x32_bf16 v[122:125], v[172:175], v[184:187], v[122:125]
	v_mfma_f32_16x16x32_bf16 v[102:105], v[150:153], v[192:195], v[102:105]
	v_mfma_f32_16x16x32_bf16 v[98:101], v[172:175], v[192:195], v[98:101]
	v_mfma_f32_16x16x32_bf16 v[86:89], v[150:153], v[200:203], v[86:89]
	v_mfma_f32_16x16x32_bf16 v[82:85], v[172:175], v[200:203], v[82:85]
	v_mfma_f32_16x16x32_bf16 v[70:73], v[150:153], v[230:233], v[70:73]
	v_mfma_f32_16x16x32_bf16 v[66:69], v[172:175], v[230:233], v[66:69]
	s_setprio 0
	s_barrier
	s_add_i32 s47, s88, s6
	v_lshl_add_u64 v[204:205], s[40:41], 0, v[0:1]
	s_mov_b32 m0, s47
	global_load_lds_dwordx4 v[204:205], off
	s_add_i32 m0, s47, 0x2000
	s_add_u32 s50, s40, 0x80000
	v_lshl_add_u64 v[212:213], s[40:41], 0, v[154:155]
	s_addc_u32 s51, s41, 0
	s_add_i32 s47, s89, s6
	global_load_lds_dwordx4 v[212:213], off
	v_lshl_add_u64 v[234:235], s[50:51], 0, v[0:1]
	s_mov_b32 m0, s47
	v_lshl_add_u64 v[236:237], s[42:43], 0, v[156:157]
	global_load_lds_dwordx4 v[234:235], off
	v_lshl_add_u64 v[234:235], s[50:51], 0, v[154:155]
	s_add_i32 m0, s47, 0x2000
	s_nop 0
	global_load_lds_dwordx4 v[234:235], off
	v_lshl_add_u64 v[234:235], s[42:43], 0, v[158:159]
	s_mov_b32 m0, s8
	s_nop 0
	global_load_lds_dwordx4 v[234:235], off
	s_mov_b32 m0, s9
	s_nop 0
	global_load_lds_dwordx4 v[236:237], off
	s_waitcnt vmcnt(8)
	s_waitcnt lgkmcnt(0)
	s_barrier
	s_setprio 1
	s_waitcnt lgkmcnt(0)
	s_setprio 0
	s_setprio 1
	s_setprio 0
	s_barrier
; #define PG8_STAGE(bufoff, gbase, voff) do { _Pragma("unroll") for (int _i = 0; _i < 2; ++_i) \
;         __builtin_amdgcn_global_load_lds((const unsigned*)((const char*)(gbase) + (voff)[_i]), (PG8_LAS unsigned*)(lds + (bufoff) + ldsw + _i * 8192), 16, 0, 0); } while (0)
; #define PG8_LDA(dst, b, h) do { _Pragma("unroll") for (int m = 0; m < 4; ++m) _Pragma("unroll") for (int k = 0; k < 2; ++k) dst[m][k] = *(const PG8_LAS bf16x8*)(lds + PG8_SA(b, h) + aoff + m * 2048 + k * 1024); } while (0)
; #define PG8_LDB(dst, b, h) do { _Pragma("unroll") for (int n = 0; n < 2; ++n) _Pragma("unroll") for (int k = 0; k < 2; ++k) dst[n][k] = *(const PG8_LAS bf16x8*)(lds + PG8_SB(b, h) + boff + n * 2048 + k * 1024); } while (0)
; #define PG8_MMA(ai, bj, At, Bt) do { __builtin_amdgcn_s_setprio(1); _Pragma("unroll") for (int m = 0; m < 4; ++m) _Pragma("unroll") for (int n = 0; n < 2; ++n) _Pragma("unroll") for (int k = 0; k < 2; ++k) \
;         acc[ai][bj][m][n] = __builtin_amdgcn_mfma_f32_16x16x32_bf16(Bt[n][k], At[m][k], acc[ai][bj][m][n], 0, 0, 0); __builtin_amdgcn_s_setprio(0); } while (0)
; #define PG8_WAIT_V(n) asm volatile("s_waitcnt vmcnt(" #n ")" ::: "memory")
; #define PG8_WAIT_L(n) asm volatile("s_waitcnt lgkmcnt(" #n ")" ::: "memory")
; #define PG8_BAR __builtin_amdgcn_s_barrier()
; #define PG8_SCHED __builtin_amdgcn_sched_barrier(0)
; template <class Epi, class Sched, bool ALIGN_EPI = false, bool SP2 = false>
; __device__ __forceinline__ void gemm_phase(PG8_LAS unsigned char* lds, const Gemm g, const Sched& S, const Epi& E) {
;     ...
;             PG8_LDB(B0, 1, 0); PG8_LDB(B1, 1, 1); PG8_SCHED; PG8_LDA(At, 1, 0); PG8_STAGE(PG8_SA(0, 1), a2 + hstep, voffA);
;             PG8_WAIT_V(8); PG8_WAIT_L(0); PG8_BAR; PG8_MMA(0, 0, At, B0); PG8_MMA(0, 1, At, B1); PG8_BAR; PG8_SCHED;
;             PG8_LDA(At, 1, 1); PG8_STAGE(PG8_SB(1, 0), b3, voffB); PG8_STAGE(PG8_SB(1, 1), b3 + hstep, voffB); PG8_STAGE(PG8_SA(1, 0), a3, voffA);
;             PG8_WAIT_V(8); PG8_WAIT_L(0); PG8_BAR; PG8_MMA(1, 0, At, B0); PG8_MMA(1, 1, At, B1); PG8_BAR; PG8_SCHED;
	s_add_i32 s47, 0, 0x1c000
	v_add_u32_e32 v134, s90, v177
	v_add_u32_e32 v172, s47, v177
	ds_read_b128 v[114:117], v134
	ds_read_b128 v[118:121], v134 offset:1024
	ds_read_b128 v[130:133], v134 offset:2048
	ds_read_b128 v[134:137], v134 offset:3072
	ds_read_b128 v[146:149], v172
	ds_read_b128 v[150:153], v172 offset:1024
	ds_read_b128 v[168:171], v172 offset:2048
	ds_read_b128 v[172:175], v172 offset:3072
	s_add_u32 s42, s42, 0x80000
	s_addc_u32 s43, s43, 0
	s_mov_b32 m0, s10
	v_lshl_add_u64 v[238:239], s[42:43], 0, v[158:159]
	ds_read_b128 v[180:183], v178 offset:32768
	ds_read_b128 v[184:187], v178 offset:33792
	ds_read_b128 v[188:191], v178 offset:34816
	ds_read_b128 v[192:195], v178 offset:35840
	ds_read_b128 v[196:199], v178 offset:36864
	ds_read_b128 v[200:203], v178 offset:37888
	ds_read_b128 v[208:211], v178 offset:38912
	ds_read_b128 v[230:233], v178 offset:39936
	global_load_lds_dwordx4 v[238:239], off
	v_lshl_add_u64 v[238:239], s[42:43], 0, v[156:157]
	s_mov_b32 m0, s11
	s_nop 0
	global_load_lds_dwordx4 v[238:239], off
	s_waitcnt vmcnt(8)
	s_waitcnt lgkmcnt(0)
	s_barrier
	s_setprio 1
	s_waitcnt lgkmcnt(0)
	v_mfma_f32_16x16x32_bf16 v[142:145], v[114:117], v[180:183], v[142:145]
	v_mfma_f32_16x16x32_bf16 v[138:141], v[130:133], v[180:183], v[138:141]
	v_mfma_f32_16x16x32_bf16 v[110:113], v[114:117], v[188:191], v[110:113]
	v_mfma_f32_16x16x32_bf16 v[106:109], v[130:133], v[188:191], v[106:109]
	v_mfma_f32_16x16x32_bf16 v[94:97], v[114:117], v[196:199], v[94:97]
	v_mfma_f32_16x16x32_bf16 v[90:93], v[130:133], v[196:199], v[90:93]
	v_mfma_f32_16x16x32_bf16 v[78:81], v[114:117], v[208:211], v[78:81]
	v_mfma_f32_16x16x32_bf16 v[74:77], v[130:133], v[208:211], v[74:77]
	v_mfma_f32_16x16x32_bf16 v[142:145], v[118:121], v[184:187], v[142:145]
	v_mfma_f32_16x16x32_bf16 v[138:141], v[134:137], v[184:187], v[138:141]
	v_mfma_f32_16x16x32_bf16 v[110:113], v[118:121], v[192:195], v[110:113]
	v_mfma_f32_16x16x32_bf16 v[106:109], v[134:137], v[192:195], v[106:109]
	v_mfma_f32_16x16x32_bf16 v[94:97], v[118:121], v[200:203], v[94:97]
	v_mfma_f32_16x16x32_bf16 v[90:93], v[134:137], v[200:203], v[90:93]
	v_mfma_f32_16x16x32_bf16 v[78:81], v[118:121], v[230:233], v[78:81]
	v_mfma_f32_16x16x32_bf16 v[74:77], v[134:137], v[230:233], v[74:77]
	s_setprio 0
	s_setprio 1
	v_mfma_f32_16x16x32_bf16 v[126:129], v[146:149], v[180:183], v[126:129]
	v_mfma_f32_16x16x32_bf16 v[122:125], v[168:171], v[180:183], v[122:125]
	v_mfma_f32_16x16x32_bf16 v[102:105], v[146:149], v[188:191], v[102:105]
	v_mfma_f32_16x16x32_bf16 v[98:101], v[168:171], v[188:191], v[98:101]
	v_mfma_f32_16x16x32_bf16 v[86:89], v[146:149], v[196:199], v[86:89]
	v_mfma_f32_16x16x32_bf16 v[82:85], v[168:171], v[196:199], v[82:85]
	v_mfma_f32_16x16x32_bf16 v[70:73], v[146:149], v[208:211], v[70:73]
	v_mfma_f32_16x16x32_bf16 v[66:69], v[168:171], v[208:211], v[66:69]
	v_mfma_f32_16x16x32_bf16 v[126:129], v[150:153], v[184:187], v[126:129]
	v_mfma_f32_16x16x32_bf16 v[122:125], v[172:175], v[184:187], v[122:125]
	v_mfma_f32_16x16x32_bf16 v[102:105], v[150:153], v[192:195], v[102:105]
	v_mfma_f32_16x16x32_bf16 v[98:101], v[172:175], v[192:195], v[98:101]
	v_mfma_f32_16x16x32_bf16 v[86:89], v[150:153], v[200:203], v[86:89]
	v_mfma_f32_16x16x32_bf16 v[82:85], v[172:175], v[200:203], v[82:85]
	v_mfma_f32_16x16x32_bf16 v[70:73], v[150:153], v[230:233], v[70:73]
	v_mfma_f32_16x16x32_bf16 v[66:69], v[172:175], v[230:233], v[66:69]
	s_setprio 0
	s_barrier
	s_add_i32 s42, s90, s6
	v_lshl_add_u64 v[204:205], v[204:205], 0, s[70:71]
	s_mov_b32 m0, s42
	global_load_lds_dwordx4 v[204:205], off
	s_add_i32 m0, s42, 0x2000
	s_add_u32 s40, s40, 0x80080
	v_lshl_add_u64 v[204:205], v[212:213], 0, s[70:71]
	s_addc_u32 s41, s41, 0
	s_add_i32 s42, s47, s6
	global_load_lds_dwordx4 v[204:205], off
	v_lshl_add_u64 v[204:205], s[40:41], 0, v[0:1]
	s_mov_b32 m0, s42
	s_nop 0
	global_load_lds_dwordx4 v[204:205], off
	v_lshl_add_u64 v[204:205], s[40:41], 0, v[154:155]
	s_add_i32 m0, s42, 0x2000
	s_nop 0
	global_load_lds_dwordx4 v[204:205], off
	v_lshl_add_u64 v[204:205], v[234:235], 0, s[70:71]
	s_mov_b32 m0, s13
	s_nop 0
	global_load_lds_dwordx4 v[204:205], off
	v_lshl_add_u64 v[204:205], v[236:237], 0, s[70:71]
	s_mov_b32 m0, s25
	s_nop 0
	global_load_lds_dwordx4 v[204:205], off
	s_waitcnt vmcnt(8)
	s_waitcnt lgkmcnt(0)
	s_barrier
	s_setprio 1
	s_waitcnt lgkmcnt(0)
	s_setprio 0
	s_setprio 1
	s_setprio 0
	s_barrier
	s_add_i32 s46, s46, 2
	s_add_u32 s34, s34, 0x100
	s_addc_u32 s35, s35, 0
	s_add_u32 s44, s44, 0x100
	s_addc_u32 s45, s45, 0
	s_cmp_gt_u32 s46, 29
	s_cbranch_scc0 .Ltail_loop
	s_branch .Ltail_join
